# 32x32x16 attention loop: PV pipelined at 16-key granularity (tail of 4 MFMAs), 8 V fragment slots
# speedup vs baseline: 1.0213x; 1.0025x over previous
.Lattn_nf_loop:
	s_and_b32 s10, s15, 1
	s_mul_i32 s6, s10, 0x8800
	v_add_u32_e32 v136, s6, v137
	v_add_u32_e32 v170, s6, v183
	s_sub_u32 s10, 0x8800, s6
	ds_read_b128 v[98:101], v136 offset:0
	ds_read_b128 v[102:105], v136 offset:32
	ds_read_b128 v[106:109], v136 offset:64
	ds_read_b128 v[110:113], v136 offset:96
	v_add_u32_e32 v171, s10, v126
	v_add_u32_e32 v173, s10, v127
	global_load_dwordx4 v[82:85], v124, s[64:65]
	global_load_dwordx4 v[86:89], v124, s[66:67]
	global_load_dwordx4 v[90:93], v124, s[68:69]
	global_load_dwordx4 v[94:97], v124, s[70:71]
	v_add_u32_e32 v124, s36, v124
	s_waitcnt lgkmcnt(3)
	v_mfma_f32_32x32x16_bf16 v[138:153], v[98:101], v[10:13], 0
	ds_read_b128 v[98:101], v136 offset:8704
	s_waitcnt lgkmcnt(3)
	v_mfma_f32_32x32x16_bf16 v[138:153], v[102:105], v[14:17], v[138:153]
	ds_read_b128 v[102:105], v136 offset:8736
	s_waitcnt lgkmcnt(3)
	v_mfma_f32_32x32x16_bf16 v[138:153], v[106:109], v[2:5], v[138:153]
	ds_read_b128 v[106:109], v136 offset:8768
	s_waitcnt lgkmcnt(3)
	v_mfma_f32_32x32x16_bf16 v[138:153], v[110:113], v[6:9], v[138:153]
	ds_read_b128 v[110:113], v136 offset:8800
	ds_read_b128 v[128:131], v170 offset:0
	ds_read_b128 v[184:187], v170 offset:8704
	ds_read_b128 v[188:191], v170 offset:17408
	ds_read_b128 v[192:195], v170 offset:26112
	s_waitcnt lgkmcnt(7)
	v_mfma_f32_32x32x16_bf16 v[154:169], v[98:101], v[10:13], 0
	ds_read_b128 v[98:101], v136 offset:17408
	s_nop 3
	v_exp_f32_e32 v138, v138
	v_exp_f32_e32 v139, v139
	v_exp_f32_e32 v140, v140
	v_exp_f32_e32 v141, v141
	v_exp_f32_e32 v142, v142
	v_exp_f32_e32 v143, v143
	v_exp_f32_e32 v144, v144
	v_exp_f32_e32 v145, v145
	s_waitcnt lgkmcnt(7)
	v_mfma_f32_32x32x16_bf16 v[154:169], v[102:105], v[14:17], v[154:169]
	ds_read_b128 v[102:105], v136 offset:17440
	v_add_f32_e32 v122, v138, v122
	v_add_f32_e32 v122, v139, v122
	v_add_f32_e32 v122, v140, v122
	v_add_f32_e32 v122, v141, v122
	v_add_f32_e32 v122, v142, v122
	v_add_f32_e32 v122, v143, v122
	v_add_f32_e32 v122, v144, v122
	v_add_f32_e32 v122, v145, v122
	v_cvt_pk_bf16_f32 v114, v138, v139
	v_cvt_pk_bf16_f32 v115, v140, v141
	v_cvt_pk_bf16_f32 v116, v142, v143
	v_cvt_pk_bf16_f32 v117, v144, v145
	ds_read_b128 v[196:199], v170 offset:32
	ds_read_b128 v[216:219], v170 offset:8736
	ds_read_b128 v[200:203], v170 offset:17440
	ds_read_b128 v[204:207], v170 offset:26144
	s_waitcnt lgkmcnt(11)
	v_mfma_f32_32x32x16_bf16 v[154:169], v[106:109], v[2:5], v[154:169]
	ds_read_b128 v[106:109], v136 offset:17472
	v_exp_f32_e32 v146, v146
	v_exp_f32_e32 v147, v147
	v_exp_f32_e32 v148, v148
	s_waitcnt lgkmcnt(11)
	v_mfma_f32_32x32x16_bf16 v[154:169], v[110:113], v[6:9], v[154:169]
	ds_read_b128 v[110:113], v136 offset:17504
	v_exp_f32_e32 v149, v149
	v_exp_f32_e32 v150, v150
	v_exp_f32_e32 v151, v151
	s_waitcnt lgkmcnt(11)
	v_mfma_f32_32x32x16_bf16 v[18:33], v[128:131], v[114:117], v[18:33]
	v_exp_f32_e32 v152, v152
	v_exp_f32_e32 v153, v153
	v_add_f32_e32 v122, v146, v122
	s_waitcnt lgkmcnt(10)
	v_mfma_f32_32x32x16_bf16 v[34:49], v[184:187], v[114:117], v[34:49]
	v_add_f32_e32 v122, v147, v122
	v_add_f32_e32 v122, v148, v122
	v_add_f32_e32 v122, v149, v122
	s_waitcnt lgkmcnt(9)
	v_mfma_f32_32x32x16_bf16 v[50:65], v[188:191], v[114:117], v[50:65]
	v_add_f32_e32 v122, v150, v122
	v_add_f32_e32 v122, v151, v122
	s_waitcnt lgkmcnt(8)
	v_mfma_f32_32x32x16_bf16 v[66:81], v[192:195], v[114:117], v[66:81]
	v_add_f32_e32 v122, v152, v122
	v_add_f32_e32 v122, v153, v122
	v_cvt_pk_bf16_f32 v118, v146, v147
	v_cvt_pk_bf16_f32 v119, v148, v149
	v_cvt_pk_bf16_f32 v120, v150, v151
	v_cvt_pk_bf16_f32 v121, v152, v153
	ds_read_b128 v[128:131], v170 offset:64
	ds_read_b128 v[184:187], v170 offset:8768
	ds_read_b128 v[188:191], v170 offset:17472
	ds_read_b128 v[192:195], v170 offset:26176
	s_waitcnt lgkmcnt(11)
	v_mfma_f32_32x32x16_bf16 v[138:153], v[98:101], v[10:13], 0
	ds_read_b128 v[98:101], v136 offset:26112
	v_exp_f32_e32 v154, v154
	v_exp_f32_e32 v155, v155
	v_exp_f32_e32 v156, v156
	s_waitcnt lgkmcnt(11)
	v_mfma_f32_32x32x16_bf16 v[138:153], v[102:105], v[14:17], v[138:153]
	ds_read_b128 v[102:105], v136 offset:26144
	v_exp_f32_e32 v157, v157
	v_exp_f32_e32 v158, v158
	v_exp_f32_e32 v159, v159
	s_waitcnt lgkmcnt(11)
	v_mfma_f32_32x32x16_bf16 v[18:33], v[196:199], v[118:121], v[18:33]
	v_exp_f32_e32 v160, v160
	v_exp_f32_e32 v161, v161
	v_add_f32_e32 v122, v154, v122
	s_waitcnt lgkmcnt(10)
	v_mfma_f32_32x32x16_bf16 v[34:49], v[216:219], v[118:121], v[34:49]
	v_add_f32_e32 v122, v155, v122
	v_add_f32_e32 v122, v156, v122
	v_add_f32_e32 v122, v157, v122
	s_waitcnt lgkmcnt(9)
	v_mfma_f32_32x32x16_bf16 v[50:65], v[200:203], v[118:121], v[50:65]
	v_add_f32_e32 v122, v158, v122
	v_add_f32_e32 v122, v159, v122
	s_waitcnt lgkmcnt(8)
	v_mfma_f32_32x32x16_bf16 v[66:81], v[204:207], v[118:121], v[66:81]
	v_add_f32_e32 v122, v160, v122
	v_add_f32_e32 v122, v161, v122
	v_cvt_pk_bf16_f32 v114, v154, v155
	v_cvt_pk_bf16_f32 v115, v156, v157
	v_cvt_pk_bf16_f32 v116, v158, v159
	v_cvt_pk_bf16_f32 v117, v160, v161
	ds_read_b128 v[196:199], v170 offset:96
	ds_read_b128 v[216:219], v170 offset:8800
	ds_read_b128 v[200:203], v170 offset:17504
	ds_read_b128 v[204:207], v170 offset:26208
	s_waitcnt lgkmcnt(11)
	v_mfma_f32_32x32x16_bf16 v[138:153], v[106:109], v[2:5], v[138:153]
	ds_read_b128 v[106:109], v136 offset:26176
	v_exp_f32_e32 v162, v162
	v_exp_f32_e32 v163, v163
	v_exp_f32_e32 v164, v164
	s_waitcnt lgkmcnt(11)
	v_mfma_f32_32x32x16_bf16 v[138:153], v[110:113], v[6:9], v[138:153]
	ds_read_b128 v[110:113], v136 offset:26208
	v_exp_f32_e32 v165, v165
	v_exp_f32_e32 v166, v166
	v_exp_f32_e32 v167, v167
	s_waitcnt lgkmcnt(11)
	v_mfma_f32_32x32x16_bf16 v[18:33], v[128:131], v[114:117], v[18:33]
	v_exp_f32_e32 v168, v168
	v_exp_f32_e32 v169, v169
	v_add_f32_e32 v122, v162, v122
	s_waitcnt lgkmcnt(10)
	v_mfma_f32_32x32x16_bf16 v[34:49], v[184:187], v[114:117], v[34:49]
	v_add_f32_e32 v122, v163, v122
	v_add_f32_e32 v122, v164, v122
	v_add_f32_e32 v122, v165, v122
	s_waitcnt lgkmcnt(9)
	v_mfma_f32_32x32x16_bf16 v[50:65], v[188:191], v[114:117], v[50:65]
	v_add_f32_e32 v122, v166, v122
	v_add_f32_e32 v122, v167, v122
	s_waitcnt lgkmcnt(8)
	v_mfma_f32_32x32x16_bf16 v[66:81], v[192:195], v[114:117], v[66:81]
	v_add_f32_e32 v122, v168, v122
	v_add_f32_e32 v122, v169, v122
	v_cvt_pk_bf16_f32 v118, v162, v163
	v_cvt_pk_bf16_f32 v119, v164, v165
	v_cvt_pk_bf16_f32 v120, v166, v167
	v_cvt_pk_bf16_f32 v121, v168, v169
	ds_read_b128 v[128:131], v170 offset:128
	ds_read_b128 v[184:187], v170 offset:8832
	ds_read_b128 v[188:191], v170 offset:17536
	ds_read_b128 v[192:195], v170 offset:26240
	s_waitcnt lgkmcnt(11)
	v_mfma_f32_32x32x16_bf16 v[154:169], v[98:101], v[10:13], 0
	v_exp_f32_e32 v138, v138
	v_exp_f32_e32 v139, v139
	v_exp_f32_e32 v140, v140
	s_waitcnt lgkmcnt(10)
	v_mfma_f32_32x32x16_bf16 v[154:169], v[102:105], v[14:17], v[154:169]
	v_exp_f32_e32 v141, v141
	v_exp_f32_e32 v142, v142
	v_exp_f32_e32 v143, v143
	s_waitcnt lgkmcnt(9)
	v_mfma_f32_32x32x16_bf16 v[18:33], v[196:199], v[118:121], v[18:33]
	v_exp_f32_e32 v144, v144
	v_exp_f32_e32 v145, v145
	s_waitcnt vmcnt(3)
	ds_write_b128 v171, v[82:85] offset:0
	s_waitcnt vmcnt(2)
	ds_write_b128 v171, v[86:89] offset:8704
	s_waitcnt vmcnt(1)
	ds_write_b128 v171, v[90:93] offset:17408
	s_waitcnt vmcnt(0)
	ds_write_b128 v171, v[94:97] offset:26112
	v_add_f32_e32 v122, v138, v122
	v_add_f32_e32 v122, v139, v122
	s_waitcnt lgkmcnt(12)
	v_mfma_f32_32x32x16_bf16 v[34:49], v[216:219], v[118:121], v[34:49]
	v_add_f32_e32 v122, v140, v122
	v_add_f32_e32 v122, v141, v122
	s_waitcnt lgkmcnt(11)
	v_mfma_f32_32x32x16_bf16 v[50:65], v[200:203], v[118:121], v[50:65]
	v_add_f32_e32 v122, v142, v122
	v_add_f32_e32 v122, v143, v122
	s_waitcnt lgkmcnt(10)
	v_mfma_f32_32x32x16_bf16 v[66:81], v[204:207], v[118:121], v[66:81]
	v_add_f32_e32 v122, v144, v122
	v_add_f32_e32 v122, v145, v122
	v_cvt_pk_bf16_f32 v114, v138, v139
	v_cvt_pk_bf16_f32 v115, v140, v141
	v_cvt_pk_bf16_f32 v116, v142, v143
	v_cvt_pk_bf16_f32 v117, v144, v145
	ds_read_b128 v[196:199], v170 offset:160
	ds_read_b128 v[216:219], v170 offset:8864
	ds_read_b128 v[200:203], v170 offset:17568
	ds_read_b128 v[204:207], v170 offset:26272
	s_waitcnt lgkmcnt(13)
	v_mfma_f32_32x32x16_bf16 v[154:169], v[106:109], v[2:5], v[154:169]
	v_exp_f32_e32 v146, v146
	v_exp_f32_e32 v147, v147
	v_exp_f32_e32 v148, v148
	s_waitcnt lgkmcnt(12)
	v_mfma_f32_32x32x16_bf16 v[154:169], v[110:113], v[6:9], v[154:169]
	v_exp_f32_e32 v149, v149
	v_exp_f32_e32 v150, v150
	v_exp_f32_e32 v151, v151
	s_waitcnt lgkmcnt(11)
	v_mfma_f32_32x32x16_bf16 v[18:33], v[128:131], v[114:117], v[18:33]
	v_exp_f32_e32 v152, v152
	v_exp_f32_e32 v153, v153
	global_load_dwordx4 v[82:85], v125, s[72:73]
	global_load_dwordx4 v[86:89], v125, s[74:75]
	global_load_dwordx4 v[90:93], v125, s[76:77]
	global_load_dwordx4 v[94:97], v125, s[78:79]
	v_add_u32_e32 v125, s38, v125
	v_add_f32_e32 v122, v146, v122
	v_add_f32_e32 v122, v147, v122
	s_waitcnt lgkmcnt(10)
	v_mfma_f32_32x32x16_bf16 v[34:49], v[184:187], v[114:117], v[34:49]
	v_add_f32_e32 v122, v148, v122
	v_add_f32_e32 v122, v149, v122
	s_waitcnt lgkmcnt(9)
	v_mfma_f32_32x32x16_bf16 v[50:65], v[188:191], v[114:117], v[50:65]
	v_add_f32_e32 v122, v150, v122
	v_add_f32_e32 v122, v151, v122
	s_waitcnt lgkmcnt(8)
	v_mfma_f32_32x32x16_bf16 v[66:81], v[192:195], v[114:117], v[66:81]
	v_add_f32_e32 v122, v152, v122
	v_add_f32_e32 v122, v153, v122
	v_cvt_pk_bf16_f32 v118, v146, v147
	v_cvt_pk_bf16_f32 v119, v148, v149
	v_cvt_pk_bf16_f32 v120, v150, v151
	v_cvt_pk_bf16_f32 v121, v152, v153
	ds_read_b128 v[128:131], v170 offset:192
	ds_read_b128 v[184:187], v170 offset:8896
	ds_read_b128 v[188:191], v170 offset:17600
	ds_read_b128 v[192:195], v170 offset:26304
	s_waitcnt lgkmcnt(7)
	v_mfma_f32_32x32x16_bf16 v[18:33], v[196:199], v[118:121], v[18:33]
	v_exp_f32_e32 v154, v154
	v_exp_f32_e32 v155, v155
	v_exp_f32_e32 v156, v156
	v_exp_f32_e32 v157, v157
	s_waitcnt lgkmcnt(6)
	v_mfma_f32_32x32x16_bf16 v[34:49], v[216:219], v[118:121], v[34:49]
	v_exp_f32_e32 v158, v158
	v_exp_f32_e32 v159, v159
	v_exp_f32_e32 v160, v160
	v_exp_f32_e32 v161, v161
	s_waitcnt lgkmcnt(5)
	v_mfma_f32_32x32x16_bf16 v[50:65], v[200:203], v[118:121], v[50:65]
	v_add_f32_e32 v122, v154, v122
	v_add_f32_e32 v122, v155, v122
	v_add_f32_e32 v122, v156, v122
	v_add_f32_e32 v122, v157, v122
	s_waitcnt lgkmcnt(4)
	v_mfma_f32_32x32x16_bf16 v[66:81], v[204:207], v[118:121], v[66:81]
	v_add_f32_e32 v122, v158, v122
	v_add_f32_e32 v122, v159, v122
	v_add_f32_e32 v122, v160, v122
	v_add_f32_e32 v122, v161, v122
	v_cvt_pk_bf16_f32 v114, v154, v155
	v_cvt_pk_bf16_f32 v115, v156, v157
	v_cvt_pk_bf16_f32 v116, v158, v159
	v_cvt_pk_bf16_f32 v117, v160, v161
	ds_read_b128 v[196:199], v170 offset:224
	ds_read_b128 v[216:219], v170 offset:8928
	ds_read_b128 v[200:203], v170 offset:17632
	ds_read_b128 v[204:207], v170 offset:26336
	s_waitcnt lgkmcnt(7)
	v_mfma_f32_32x32x16_bf16 v[18:33], v[128:131], v[114:117], v[18:33]
	v_exp_f32_e32 v162, v162
	v_exp_f32_e32 v163, v163
	v_exp_f32_e32 v164, v164
	v_exp_f32_e32 v165, v165
	s_waitcnt lgkmcnt(6)
	v_mfma_f32_32x32x16_bf16 v[34:49], v[184:187], v[114:117], v[34:49]
	v_exp_f32_e32 v166, v166
	v_exp_f32_e32 v167, v167
	v_exp_f32_e32 v168, v168
	v_exp_f32_e32 v169, v169
	s_waitcnt lgkmcnt(5)
	v_mfma_f32_32x32x16_bf16 v[50:65], v[188:191], v[114:117], v[50:65]
	v_add_f32_e32 v122, v162, v122
	v_add_f32_e32 v122, v163, v122
	v_add_f32_e32 v122, v164, v122
	v_add_f32_e32 v122, v165, v122
	s_waitcnt lgkmcnt(4)
	v_mfma_f32_32x32x16_bf16 v[66:81], v[192:195], v[114:117], v[66:81]
	v_add_f32_e32 v122, v166, v122
	v_add_f32_e32 v122, v167, v122
	v_add_f32_e32 v122, v168, v122
	v_add_f32_e32 v122, v169, v122
	v_cvt_pk_bf16_f32 v118, v162, v163
	v_cvt_pk_bf16_f32 v119, v164, v165
	v_cvt_pk_bf16_f32 v120, v166, v167
	v_cvt_pk_bf16_f32 v121, v168, v169
	s_waitcnt lgkmcnt(3)
	s_nop 0
	v_mfma_f32_32x32x16_bf16 v[18:33], v[196:199], v[118:121], v[18:33]
	s_waitcnt lgkmcnt(2)
	v_mfma_f32_32x32x16_bf16 v[34:49], v[216:219], v[118:121], v[34:49]
	s_waitcnt vmcnt(3)
	ds_write_b128 v173, v[82:85] offset:0
	s_waitcnt vmcnt(2)
	ds_write_b128 v173, v[86:89] offset:8704
	s_waitcnt vmcnt(1)
	ds_write_b128 v173, v[90:93] offset:17408
	s_waitcnt vmcnt(0)
	ds_write_b128 v173, v[94:97] offset:26112
	s_waitcnt lgkmcnt(5)
	v_mfma_f32_32x32x16_bf16 v[50:65], v[200:203], v[118:121], v[50:65]
	s_waitcnt lgkmcnt(4)
	v_mfma_f32_32x32x16_bf16 v[66:81], v[204:207], v[118:121], v[66:81]
	s_waitcnt lgkmcnt(0)
	s_barrier
	s_add_i32 s15, s15, 1
	s_cmp_eq_u32 s15, 34
	s_cbranch_scc0 .Lattn_nf_loop
	v_readlane_b32 s64, v175, 0
	v_readlane_b32 s65, v175, 1
	v_readlane_b32 s66, v175, 2
	v_readlane_b32 s67, v175, 3
	v_readlane_b32 s68, v175, 4
	v_readlane_b32 s69, v175, 5
	v_readlane_b32 s70, v175, 6
	v_readlane_b32 s71, v175, 7
	v_readlane_b32 s72, v175, 8
	v_readlane_b32 s73, v175, 9
	v_readlane_b32 s74, v175, 10
	v_readlane_b32 s75, v175, 11
	v_readlane_b32 s76, v175, 12
	v_readlane_b32 s77, v175, 13
	v_readlane_b32 s78, v175, 14
	v_readlane_b32 s79, v175, 15
	s_nop 4
	v_add_f32_e32 v186, v132, v134
	v_add_f32_e32 v184, v133, v135
	ds_bpermute_b32 v187, v172, v186
	ds_bpermute_b32 v185, v172, v184
	s_mov_b32 s10, 0x3fb8aa3b
	s_mov_b32 s11, 0xc2ce8ed0
	s_mov_b32 s6, 0x42b17218
	v_cmp_eq_u32_e64 s[40:41], 0, v179
	s_lshl_b32 s30, s14, 1
	v_lshlrev_b32_e32 v196, 3, v178
	v_mov_b32_e32 v197, 0
	v_lshlrev_b32_e32 v198, 4, v179
	v_or3_b32 v198, v198, v177, v180
	v_ashrrev_i32_e32 v199, 31, v198
	v_lshlrev_b64 v[198:199], 11, v[198:199]
	s_mov_b64 s[100:101], 0x18a10000
	v_lshl_add_u64 v[198:199], s[42:43], 0, v[198:199]
	v_lshl_add_u64 v[198:199], v[198:199], 0, s[30:31]
	v_lshl_add_u64 v[198:199], v[198:199], 0, v[196:197]
	v_lshl_add_u64 v[198:199], v[198:199], 0, s[100:101]
	global_load_dwordx2 v[146:147], v[198:199], off
	global_load_dwordx2 v[148:149], v[198:199], off offset:32
	global_load_dwordx2 v[150:151], v[198:199], off offset:64
	global_load_dwordx2 v[152:153], v[198:199], off offset:96
	global_load_dwordx2 v[188:189], v[198:199], off offset:128
	global_load_dwordx2 v[190:191], v[198:199], off offset:160
	global_load_dwordx2 v[192:193], v[198:199], off offset:192
	global_load_dwordx2 v[194:195], v[198:199], off offset:224
	s_mov_b64 s[100:101], exec
	s_and_b64 exec, exec, s[4:5]
	s_cbranch_execz .Lpop_skip
	v_readlane_b32 s14, v255, 22
	v_readlane_b32 s15, v255, 23
	v_mov_b32_e32 v224, 1
	s_nop 4
	global_atomic_add v224, v0, v224, s[14:15] sc0
